# local mode: conv/KV->Qup seam is arrive-only with the wait deferred to the first Q-up epilogue (WAR only, no writeback/invalidate); out->final seam XCD-local with final-pass rows remapped to the produ
# speedup vs baseline: 1.0439x; 1.0206x over previous
; __device__ __forceinline__ unsigned xb_ld(unsigned* p)              { return __hip_atomic_load(p, __ATOMIC_RELAXED, __HIP_MEMORY_SCOPE_AGENT); }
; __device__ __forceinline__ unsigned xb_add(unsigned* p, unsigned v) { return __hip_atomic_fetch_add(p, v, __ATOMIC_RELAXED, __HIP_MEMORY_SCOPE_AGENT); }
; #define XB_SPIN(cond, bar) do { unsigned _sp = 0; while (cond) { __builtin_amdgcn_s_sleep(1); \
;     if ((++_sp & 255u) == 0u) { if (xb_ld(&(bar)[XB_TMO])) break; if (_sp > XB_SPIN_CAP) { atomicAdd(&(bar)[XB_TMO], 1u); break; } } } } while (0)
; __device__ __forceinline__ void xcd_barrier(const XcdBarrier& b) {
;     asm volatile("s_waitcnt vmcnt(0)" ::: "memory");
;     __syncthreads();
;     if (threadIdx.x == 0) {
;         unsigned* bar = b.bar;
;         __builtin_amdgcn_s_waitcnt(0);
;         unsigned nloc = b.st[0], nx = b.st[1];
;         if (nloc == 0u) { xcd_barrier_complete(bar, b.x, nloc, nx); b.st[0] = nloc; b.st[1] = nx; }
;         const unsigned old = xb_add(&bar[XB_XSUB(b.x)], 1u);
;         const unsigned gen = old / nloc;
;         if (old + 1u == (gen + 1u) * nloc) {
;             __builtin_amdgcn_fence(__ATOMIC_RELEASE, "agent");
;             asm volatile("s_waitcnt vmcnt(0)" ::: "memory");
;             const unsigned og = xb_add(&bar[XB_TOP], 1u);
;             const unsigned tg = og / nx;
;             if (og + 1u == (tg + 1u) * nx) xb_add(&bar[XB_TOPGEN], 1u);
;             else XB_SPIN(xb_ld(&bar[XB_TOPGEN]) == tg, bar);
.LBB0_1320:
	s_cmp_gt_i32 s93, 6
	s_cselect_b64 s[0:1], -1, 0
	s_and_b64 s[2:3], s[4:5], s[0:1]
	s_andn2_b64 vcc, exec, s[2:3]
	s_cbranch_vccnz .LBB0_1374
	s_waitcnt vmcnt(0)
	s_waitcnt lgkmcnt(0)
	s_barrier
	s_mov_b64 s[2:3], exec
	v_readlane_b32 s4, v254, 5
	v_readlane_b32 s5, v254, 6
	s_and_b64 s[4:5], s[2:3], s[4:5]
	s_mov_b64 exec, s[4:5]
	s_cbranch_execz .LBB0_1373
	s_cmp_lg_u32 s98, 0
	s_cbranch_scc1 .Lfb_orig_6
	v_readlane_b32 s4, v254, 4
	v_readlane_b32 s6, v254, 2
	v_readlane_b32 s7, v254, 3
	s_lshl_b32 s4, s4, 8
	s_add_u32 s4, s6, s4
	s_addc_u32 s5, s7, 0
	v_mov_b32_e32 v0, 0
	v_mov_b32_e32 v1, 1
	v_mov_b32_e32 v2, 0
	global_atomic_add v1, v0, v1, s[4:5] offset:1088 sc0
	s_waitcnt vmcnt(0)
	v_cmp_le_u32_e32 vcc, 127, v1
	s_cbranch_vccz .Lfb_spin_6
	v_mov_b32_e32 v1, 0x73904
	v_mov_b32_e32 v2, 1
	global_atomic_add v1, v2, s[90:91]
	v_mov_b32_e32 v2, 0
	s_branch .Lfb_done_6

; __device__ __forceinline__ unsigned xb_ld(unsigned* p)              { return __hip_atomic_load(p, __ATOMIC_RELAXED, __HIP_MEMORY_SCOPE_AGENT); }
; __device__ __forceinline__ unsigned xb_add(unsigned* p, unsigned v) { return __hip_atomic_fetch_add(p, v, __ATOMIC_RELAXED, __HIP_MEMORY_SCOPE_AGENT); }
; #define XB_SPIN(cond, bar) do { unsigned _sp = 0; while (cond) { __builtin_amdgcn_s_sleep(1); \
;     if ((++_sp & 255u) == 0u) { if (xb_ld(&(bar)[XB_TMO])) break; if (_sp > XB_SPIN_CAP) { atomicAdd(&(bar)[XB_TMO], 1u); break; } } } } while (0)
; __device__ __forceinline__ void xcd_barrier(const XcdBarrier& b) {
;     asm volatile("s_waitcnt vmcnt(0)" ::: "memory");
;     __syncthreads();
;     if (threadIdx.x == 0) {
;         unsigned* bar = b.bar;
;         __builtin_amdgcn_s_waitcnt(0);
;         unsigned nloc = b.st[0], nx = b.st[1];
;         if (nloc == 0u) { xcd_barrier_complete(bar, b.x, nloc, nx); b.st[0] = nloc; b.st[1] = nx; }
;         const unsigned old = xb_add(&bar[XB_XSUB(b.x)], 1u);
;         const unsigned gen = old / nloc;
;         if (old + 1u == (gen + 1u) * nloc) {
;             __builtin_amdgcn_fence(__ATOMIC_RELEASE, "agent");
;             asm volatile("s_waitcnt vmcnt(0)" ::: "memory");
;             const unsigned og = xb_add(&bar[XB_TOP], 1u);
;             const unsigned tg = og / nx;
;             if (og + 1u == (tg + 1u) * nx) xb_add(&bar[XB_TOPGEN], 1u);
;             else XB_SPIN(xb_ld(&bar[XB_TOPGEN]) == tg, bar);
;             __builtin_amdgcn_fence(__ATOMIC_ACQUIRE, "agent");
;             xb_add(&bar[XB_XGEN(b.x)], 1u);
;             asm volatile("s_waitcnt vmcnt(0)" ::: "memory");
;         } else {
;             XB_SPIN(xb_ld(&bar[XB_XGEN(b.x)]) == gen, bar);
;             __builtin_amdgcn_fence(__ATOMIC_ACQUIRE, "agent");
;             asm volatile("s_waitcnt vmcnt(0)" ::: "memory");
;         }
.LBB0_1404:
	s_cmp_gt_i32 s93, 7
	s_cselect_b64 s[0:1], -1, 0
	s_and_b64 s[2:3], s[4:5], s[0:1]
	s_andn2_b64 vcc, exec, s[2:3]
	s_cbranch_vccnz .LBB0_1458
	s_waitcnt vmcnt(0)
	s_waitcnt vmcnt(0) lgkmcnt(0)
	s_barrier
	s_mov_b64 s[2:3], exec
	v_readlane_b32 s4, v254, 5
	v_readlane_b32 s5, v254, 6
	s_and_b64 s[4:5], s[2:3], s[4:5]
	s_mov_b64 exec, s[4:5]
	s_cbranch_execz .LBB0_1457
	s_cmp_lg_u32 s98, 0
	s_cbranch_scc1 .Lfb_orig_7
	v_readlane_b32 s4, v254, 4
	v_readlane_b32 s6, v254, 2
	v_readlane_b32 s7, v254, 3
	s_lshl_b32 s4, s4, 8
	s_add_u32 s4, s6, s4
	s_addc_u32 s5, s7, 0
	v_mov_b32_e32 v0, 0
	v_mov_b32_e32 v1, 1
	v_mov_b32_e32 v2, 0
	v_mov_b32_e32 v3, 0x73904
	global_atomic_add v1, v0, v1, s[4:5] offset:1088 sc0
	global_load_dword v4, v3, s[90:91] sc1
	s_waitcnt vmcnt(0)
	v_cmp_le_u32_e32 vcc, 159, v1
	s_cbranch_vccnz .Lfb_md_7
.Lfb_spin_7:
	global_load_dword v1, v0, s[4:5] offset:1088 sc1
	v_add_u32_e32 v2, 1, v2
	s_waitcnt vmcnt(0)
	v_cmp_le_u32_e32 vcc, 160, v1
	s_cbranch_vccnz .Lfb_md_7
	v_cmp_gt_u32_e32 vcc, 0x8000, v2
	s_cbranch_vccnz .Lfb_spin_7
.Lfb_md_7:
	v_cmp_le_u32_e32 vcc, 8, v4
	s_cbranch_vccnz .Lfb_done_7
	global_load_dword v4, v3, s[90:91] sc1
	v_add_u32_e32 v2, 1, v2
	s_waitcnt vmcnt(0)
	v_cmp_gt_u32_e32 vcc, 0x10000, v2
	s_cbranch_vccnz .Lfb_md_7

; __device__ __forceinline__ void final_pass(const Ptrs& P, int G) {
;     const int tid = threadIdx.x, lane = tid & 63, wave = tid >> 6;
;     const int gw = blockIdx.x * 8 + wave, NGW = G * 8;
;     const bf16_t* O = (const bf16_t*)(P.ws + WS_RB); const float* mod = (const float*)(P.ws + WS_MOD);
;     f32x4 gp[4];
; #pragma unroll
;     for (int j = 0; j < 4; ++j) gp[j] = *(const f32x4*)(P.g_post + 256 * j + 4 * lane);
;     for (int row0 = gw; row0 < T; row0 += 2 * NGW) {
;         u32x2 ov[2][4]; f32x4 xv[2][4], gt[2][4];
; #pragma unroll
;         for (int r = 0; r < 2; ++r) { const int row = row0 + r * NGW; if (row < T) { const int b = row >> 11;
.LBB0_1458:
	s_cmp_lt_i32 s92, 8
	s_cselect_b64 s[2:3], -1, 0
	s_and_b64 s[0:1], s[2:3], s[0:1]
	s_andn2_b64 vcc, exec, s[0:1]
	s_cbranch_vccnz .LBB0_1466
	v_lshrrev_b32_e32 v0, 6, v200
	s_waitcnt vmcnt(0)
	s_cmp_lg_u32 s98, 0
	s_cbranch_scc1 .Lfin_glob
	s_and_b32 s8, s80, 7
	s_lshl_b32 s8, s8, 12
	s_andn2_b32 s9, s80, 7
	s_add_i32 s9, s9, s8
	v_add_u32_e32 v96, s9, v0
	s_add_i32 s8, s8, 0x1000
	s_branch .Lfin_j
.Lfin_glob:
	v_lshl_add_u32 v96, s80, 3, v0
	s_mov_b32 s8, 0x8000
.Lfin_j:
	v_cmp_gt_i32_e32 vcc, s8, v96
	s_and_saveexec_b64 s[0:1], vcc
	s_cbranch_execz .LBB0_1466
	v_and_b32_e32 v17, 63, v200
	v_readlane_b32 s12, v254, 7
	v_lshlrev_b32_e32 v16, 4, v17
	v_readlane_b32 s26, v254, 21
	v_readlane_b32 s27, v254, 22
	s_nop 4
	global_load_dwordx4 v[0:3], v16, s[26:27]
	global_load_dwordx4 v[4:7], v16, s[26:27] offset:1024
	global_load_dwordx4 v[8:11], v16, s[26:27] offset:2048
	global_load_dwordx4 v[12:15], v16, s[26:27] offset:3072
	v_lshlrev_b32_e32 v18, 2, v17
	v_lshlrev_b32_e32 v80, 3, v17
	v_mbcnt_lo_u32_b32 v17, -1, 0
	v_mov_b32_e32 v81, 0
	v_mbcnt_hi_u32_b32 v17, -1, v17
	v_lshl_add_u64 v[20:21], s[90:91], 0, v[80:81]
	s_mov_b64 s[0:1], 0x9000000
	v_and_b32_e32 v19, 64, v17
	v_lshl_add_u64 v[82:83], v[20:21], 0, s[0:1]
	v_add_u32_e32 v19, 64, v19
	v_xor_b32_e32 v20, 1, v17
	v_cmp_lt_i32_e32 vcc, v20, v19
	v_readlane_b32 s14, v254, 9
	v_readlane_b32 s15, v254, 10
	v_cndmask_b32_e32 v20, v17, v20, vcc
	v_lshlrev_b32_e32 v108, 2, v20
	v_xor_b32_e32 v20, 2, v17
	v_cmp_lt_i32_e32 vcc, v20, v19
	s_lshl_b32 s9, s83, 3
	s_cmp_eq_u32 s98, 0
	s_cselect_b32 s9, 0x100, s9
	s_mov_b64 s[2:3], 0
	v_cndmask_b32_e32 v20, v17, v20, vcc
	v_lshlrev_b32_e32 v109, 2, v20
	v_xor_b32_e32 v20, 4, v17
	v_cmp_lt_i32_e32 vcc, v20, v19
	v_lshlrev_b32_e32 v80, 2, v18
	s_mov_b64 s[4:5], 0x82000
	v_cndmask_b32_e32 v20, v17, v20, vcc
	v_lshlrev_b32_e32 v110, 2, v20
	v_xor_b32_e32 v20, 8, v17
	v_cmp_lt_i32_e32 vcc, v20, v19
	s_mov_b32 s10, 0x82000
	v_mov_b32_e32 v114, 0x358637bd
	v_cndmask_b32_e32 v20, v17, v20, vcc
	v_lshlrev_b32_e32 v111, 2, v20
	v_xor_b32_e32 v20, 16, v17
	v_cmp_lt_i32_e32 vcc, v20, v19
	s_add_i32 s11, s8, -1
	v_readlane_b32 s13, v254, 8
	v_cndmask_b32_e32 v20, v17, v20, vcc
	v_lshlrev_b32_e32 v112, 2, v20
	v_xor_b32_e32 v20, 32, v17
	v_cmp_lt_i32_e32 vcc, v20, v19
	v_readlane_b32 s16, v254, 11
	v_readlane_b32 s17, v254, 12
	v_cndmask_b32_e32 v17, v17, v20, vcc
	v_lshlrev_b32_e32 v113, 2, v17
	v_mov_b32_e32 v17, v81
	v_lshl_add_u64 v[84:85], s[48:49], 0, v[16:17]
	v_lshl_add_u64 v[86:87], s[88:89], 0, v[16:17]
	v_readlane_b32 s18, v254, 13
	v_readlane_b32 s19, v254, 14
	v_readlane_b32 s20, v254, 15
	v_readlane_b32 s21, v254, 16
	v_readlane_b32 s22, v254, 17
	v_readlane_b32 s23, v254, 18
	v_readlane_b32 s24, v254, 19
	v_readlane_b32 s25, v254, 20
	s_mov_b64 s[14:15], s[26:27]
	s_branch .LBB0_1462
